# QK epilogue: align barrier placed after all of its loads (statistics and gains)
# baseline (speedup 1.0000x reference)
; #define PG8_BAR __builtin_amdgcn_s_barrier()
; template <class Epi, class Sched, bool ALIGN_EPI = false, bool SP2 = false>
; __device__ __forceinline__ void gemm_phase(PG8_LAS unsigned char* lds, const Gemm g, const Sched& S, const Epi& E) {
;     ...
;         if constexpr (ALIGN_EPI) { if (wr == 0) PG8_BAR; }
;     __device__ __forceinline__ void operator()(const f32x4 (&acc)[2][2][4][2], const pg8::Unit& u, int wr, int wc, int fr, int fq) const {
;         const int pn = u.pn, row0 = u.pm * 256 + wr * 64 + fr, col0 = pn * 256 + wc * 64 + 8 * fq;
;         const float* g = gains + (pn < 2 ? 0 : (pn < 4 ? 64 : (pn == 4 ? 128 : (pn == 5 ? 160 : 192))));
;         const int gstep = pn < 4 ? 32 : 0;
;         const float osc = (pn < 2 || pn == 6) ? 0.125f * LOG2E : (pn == 4 ? 0.17677669529663687f * LOG2E : 1.0f);
;         const float inv_n = pn < 4 ? (1.0f / 64.0f) : (1.0f / 32.0f);
;         const float* gp = g + 8 * fq;
;         u64 sv[2][4];
; #pragma unroll
;         for (int ai = 0; ai < 2; ++ai)
; #pragma unroll
;             for (int m = 0; m < 4; ++m) sv[ai][m] = ss[row0 + ai * 128 + m * 16];
;         f32x4 gg[2][2];
; #pragma unroll
;         for (int bj = 0; bj < 2; ++bj) { gg[bj][0] = *(const f32x4*)(gp + bj * gstep); gg[bj][1] = *(const f32x4*)(gp + bj * gstep + 4); }
; #pragma unroll
;         for (int ai = 0; ai < 2; ++ai)
; #pragma unroll
;             for (int m = 0; m < 4; ++m) {
;                 const int row = row0 + ai * 128 + m * 16;
;                 const float r = __builtin_amdgcn_rsqf((float)sv[ai][m] * SS_INV + 1e-6f);
;                 float s0, s1;
;                 { const f32x4 a = acc[ai][0][m][0] * r, b = acc[ai][0][m][1] * r; s0 = (a[0] * a[0] + a[1] * a[1]) + (a[2] * a[2] + a[3] * a[3]) + (b[0] * b[0] + b[1] * b[1]) + (b[2] * b[2] + b[3] * b[3]); }
;                 { const f32x4 a = acc[ai][1][m][0] * r, b = acc[ai][1][m][1] * r; s1 = (a[0] * a[0] + a[1] * a[1]) + (a[2] * a[2] + a[3] * a[3]) + (b[0] * b[0] + b[1] * b[1]) + (b[2] * b[2] + b[3] * b[3]); }
;                 if (pn < 4) { s0 += s1; s1 = s0; }
;                 s0 += __shfl_xor(s0, 16); s1 += __shfl_xor(s1, 16); s0 += __shfl_xor(s0, 32); s1 += __shfl_xor(s1, 32);
.LBB0_245:
	v_lshl_add_u32 v160, s0, 8, v177
	v_ashrrev_i32_e32 v161, 31, v160
	v_lshl_add_u64 v[98:99], v[160:161], 3, s[40:41]
	global_load_dwordx2 v[164:165], v[98:99], off
	s_cmp_eq_u32 s60, 5
	s_movk_i32 s0, 0xa0
	s_cselect_b32 s18, s0, 0xc0
	s_cmp_eq_u32 s60, 4
	s_cselect_b64 vcc, -1, 0
	s_and_b64 s[0:1], vcc, exec
	s_cselect_b32 s0, 0x80, s18
	s_cmp_gt_u32 s60, 3
	s_cselect_b32 s18, s0, 64
	s_cmp_eq_u32 s60, 6
	s_cselect_b64 s[0:1], -1, 0
	s_cmp_lt_i32 s60, 2
	s_cselect_b64 s[30:31], -1, 0
	s_and_b64 s[34:35], s[30:31], exec
	v_cndmask_b32_e32 v202, 1.0, v232, vcc
	s_cselect_b32 s18, 0, s18
	s_or_b64 vcc, s[30:31], s[0:1]
	s_cmp_lt_i32 s60, 4
	global_load_dwordx2 v[174:175], v[98:99], off offset:128
	global_load_dwordx2 v[172:173], v[98:99], off offset:256
	global_load_dwordx2 v[170:171], v[98:99], off offset:384
	global_load_dwordx2 v[168:169], v[98:99], off offset:1024
	global_load_dwordx2 v[166:167], v[98:99], off offset:1152
	global_load_dwordx2 v[162:163], v[98:99], off offset:1280
	global_load_dwordx2 v[158:159], v[98:99], off offset:1408
	s_cselect_b64 s[0:1], -1, 0
	s_and_b64 s[30:31], s[0:1], exec
	s_mov_b32 s19, s93
	s_cselect_b32 s92, 0x80, 0
	s_lshl_b32 s18, s18, 2
	v_lshl_add_u64 v[98:99], v[152:153], 0, s[18:19]
	v_lshl_add_u64 v[102:103], v[98:99], 0, s[92:93]
	global_load_dwordx4 v[106:109], v[98:99], off offset:16
	global_load_dwordx4 v[110:113], v[98:99], off
	s_nop 0
	global_load_dwordx4 v[98:101], v[102:103], off offset:16
	s_nop 0
	global_load_dwordx4 v[102:105], v[102:103], off
	s_and_b64 s[34:35], exec, s[46:47]
	s_cbranch_scc0 .Lalign_go_0
	s_barrier
.Lalign_go_0:
	v_and_b32_e32 v178, 64, v236
	v_xor_b32_e32 v176, 16, v236
	v_add_u32_e32 v178, 64, v178
	v_cmp_lt_i32_e64 s[36:37], v176, v178
	v_xor_b32_e32 v179, 32, v236
	s_cmp_lt_i32 s60, 6
	v_cndmask_b32_e64 v183, v234, v235, s[0:1]
	s_cselect_b64 s[18:19], -1, 0
	s_cmp_gt_i32 s60, 5
	s_waitcnt vmcnt(0)
	v_ffbh_u32_e32 v184, v165
	v_min_u32_e32 v184, 32, v184
	v_lshlrev_b64 v[164:165], v184, v[164:165]
	v_min_u32_e32 v164, 1, v164
	v_or_b32_e32 v164, v165, v164
	v_cvt_f32_u32_e32 v164, v164
	v_cndmask_b32_e64 v165, v236, v176, s[36:37]
	v_sub_u32_e32 v176, 32, v184
	v_cmp_lt_i32_e64 s[36:37], v179, v178
	v_ldexp_f32 v164, v164, v176
	v_fmamk_f32 v164, v164, 0x30800000, v229
	v_rsq_f32_e32 v176, v164
	v_cndmask_b32_e64 v185, v236, v179, s[36:37]
	v_lshlrev_b32_e32 v184, 2, v165
	v_lshlrev_b32_e32 v185, 2, v185
	v_pk_mul_f32 v[164:165], v[144:145], v[176:177] op_sel_hi:[1,0]
	v_pk_mul_f32 v[178:179], v[142:143], v[176:177] op_sel_hi:[1,0]
	v_pk_mul_f32 v[194:195], v[136:137], v[176:177] op_sel_hi:[1,0]
	v_pk_mul_f32 v[196:197], v[134:135], v[176:177] op_sel_hi:[1,0]
	v_pk_mul_f32 v[188:189], v[138:139], v[176:177] op_sel_hi:[1,0]
	v_pk_mul_f32 v[200:201], v[130:131], v[176:177] op_sel_hi:[1,0]
	v_mul_f32_e32 v179, v179, v179
	v_mul_f32_e32 v165, v165, v165
	v_mul_f32_e32 v197, v197, v197
	v_mul_f32_e32 v195, v195, v195
	v_pk_mul_f32 v[186:187], v[140:141], v[176:177] op_sel_hi:[1,0]
	v_pk_mul_f32 v[198:199], v[132:133], v[176:177] op_sel_hi:[1,0]
	v_mul_f32_e32 v189, v189, v189
	v_mul_f32_e32 v201, v201, v201
	v_fmac_f32_e32 v179, v178, v178
	v_fmac_f32_e32 v165, v164, v164
	v_fmac_f32_e32 v197, v196, v196
	v_fmac_f32_e32 v195, v194, v194
	v_mul_f32_e32 v187, v187, v187
	v_mul_f32_e32 v199, v199, v199
	v_fmac_f32_e32 v189, v188, v188
	v_fmac_f32_e32 v201, v200, v200
	v_add_f32_e32 v164, v179, v165
	v_add_f32_e32 v165, v197, v195
	v_fmac_f32_e32 v187, v186, v186
	v_fmac_f32_e32 v199, v198, v198
	v_add_f32_e32 v164, v189, v164
	v_add_f32_e32 v165, v201, v165
	v_add_f32_e32 v164, v187, v164
	v_add_f32_e32 v165, v199, v165
	v_add_f32_e32 v178, v164, v165
	v_cndmask_b32_e64 v165, v165, v178, s[0:1]
	v_cndmask_b32_e64 v164, v164, v178, s[0:1]
	ds_bpermute_b32 v178, v184, v164
	ds_bpermute_b32 v179, v184, v165
	v_cndmask_b32_e32 v186, v202, v233, vcc
	s_waitcnt lgkmcnt(1)
	v_add_f32_e32 v164, v164, v178
	s_waitcnt lgkmcnt(0)
	v_add_f32_e32 v165, v165, v179
	ds_bpermute_b32 v179, v185, v164
	ds_bpermute_b32 v187, v185, v165
	v_mul_f32_e32 v178, v186, v176
	v_mov_b32_e32 v176, v178
	s_cbranch_scc1 .LBB0_247
	s_waitcnt lgkmcnt(0)
	v_add_f32_e32 v165, v165, v187
	v_add_f32_e32 v164, v164, v179
	v_fmaak_f32 v164, v183, v164, 0x358637bd
	v_fmaak_f32 v165, v183, v165, 0x358637bd
	v_rsq_f32_e32 v164, v164
	v_rsq_f32_e32 v165, v165
	s_nop 0
	v_pk_mul_f32 v[178:179], v[178:179], v[164:165] op_sel_hi:[0,1]
	v_mov_b32_e32 v176, v179
